# pass B rewritten: 96 blocks x 16 state rows, f32 MFMA 16x16x4 by 4 compute waves + 4 LDS-DMA waves; gate GEMM arm gets 160 blocks (2 rounds instead of 5)
# speedup vs baseline: 1.0189x; 1.0136x over previous
.LBB0_558:
	s_cmp_lt_i32 s90, 5
	s_cselect_b64 s[2:3], -1, 0
	s_and_b64 s[0:1], s[2:3], s[0:1]
	s_andn2_b64 vcc, exec, s[0:1]
	s_cbranch_vccnz .LBB0_594
	s_cmpk_gt_i32 s33, 0x5f
	s_mov_b64 s[2:3], -1
	s_cbranch_scc0 .LBB0_589
	s_add_i32 s20, s33, 0xffffffa0
	s_cmpk_gt_u32 s20, 0x103
	v_readfirstlane_b32 s4, v188
	s_cbranch_scc1 .LBB0_588
	s_and_b32 s6, s33, 7
	s_cmp_gt_u32 s6, 3
	s_cbranch_scc0 .LBB0_563
	s_lshl_b32 s2, s6, 5
	s_or_b32 s5, s2, 4
	s_cbranch_execz .LBB0_564
	s_branch .LBB0_565

.LBB0_567:
	s_lshl_b32 s3, s3, 5
	s_mov_b64 s[8:9], 0x80
	s_and_b32 s3, s3, 0x60
	s_add_i32 m0, s26, 0x18000
	v_lshl_add_u64 v[8:9], v[8:9], 0, s[8:9]
	s_add_i32 s31, s50, 0xffffffa0
	s_lshl_b32 s5, s2, 13
	s_lshl_b32 s12, s3, 7
	s_waitcnt vmcnt(2)
	s_barrier
	global_load_lds_dwordx4 v[8:9], off
	v_lshl_add_u64 v[6:7], v[6:7], 0, s[8:9]
	s_add_i32 m0, s26, 0x1a000
	s_add_i32 s34, s26, 0x8000
	s_add_i32 s35, s26, 0xa000
	global_load_lds_dwordx4 v[6:7], off
	v_lshl_add_u64 v[2:3], v[2:3], 0, s[8:9]
	s_mov_b32 m0, s34
	s_add_u32 s10, s16, 0x18080
	global_load_lds_dwordx4 v[2:3], off
	v_lshl_add_u64 v[2:3], v[4:5], 0, s[8:9]
	s_mov_b32 m0, s35
	s_addc_u32 s11, s17, 0
	global_load_lds_dwordx4 v[2:3], off
	s_add_i32 m0, s26, 0x1c000
	v_lshl_add_u64 v[2:3], s[10:11], 0, v[132:133]
	global_load_lds_dwordx4 v[2:3], off
	v_lshl_add_u64 v[2:3], s[10:11], 0, v[136:137]
	s_add_i32 m0, s26, 0x1e000
	v_lshlrev_b32_e32 v4, 2, v188
	global_load_lds_dwordx4 v[2:3], off
	v_and_b32_e32 v2, 15, v188
	v_lshl_or_b32 v148, s2, 6, v2
	v_lshlrev_b32_e32 v3, 1, v12
	v_lshlrev_b32_e32 v5, 6, v188
	s_movk_i32 s2, 0x3c0
	v_lshl_or_b32 v2, v2, 6, v3
	v_and_b32_e32 v4, 32, v4
	v_and_or_b32 v3, v5, s2, v3
	v_bitop3_b32 v149, s12, v3, v4 bitop3:0xf6
	s_waitcnt vmcnt(6)
	s_cmpk_lt_u32 s4, 0x100
	v_add_u16_e32 v3, v10, v11
	v_bitop3_b32 v2, v2, s5, v4 bitop3:0xde
	s_cselect_b64 s[10:11], -1, 0
	v_lshrrev_b16_e32 v3, 1, v3
	s_add_i32 s37, 0, 0x10000
	s_add_i32 s38, 0, 0x14000
	s_ashr_i32 s36, s31, 31
	v_or_b32_e32 v150, s3, v12
	v_add_lshl_u32 v138, v13, v3, 1
	v_mov_b32_e32 v139, v133
	v_add_lshl_u32 v140, v14, v3, 1
	v_mov_b32_e32 v141, v133
	v_mov_b64_e32 v[142:143], 0x104
	v_mov_b64_e32 v[144:145], 0x103
	v_add_u32_e32 v151, s37, v149
	v_add_u32_e32 v152, s38, v149
	v_add_u32_e32 v153, 0, v2
	s_movk_i32 s39, 0x7fff
	s_mov_b32 s40, 0xffff0000
	s_barrier
	s_waitcnt vmcnt(0)
	s_branch .LBB0_570

.LBB0_584:
	v_lshl_add_u32 v154, s43, 8, v148
	v_ashrrev_i32_e32 v155, 31, v154
	v_lshlrev_b64 v[156:157], 11, v[154:155]
	s_nop 0
	s_nop 0
	s_nop 0
	s_nop 0
	s_nop 0
	v_cvt_pk_bf16_f32 v126, v126, v127
	s_nop 0
	s_nop 0
	s_nop 0
	s_nop 0
	s_nop 0
	v_cvt_pk_bf16_f32 v127, v128, v129
	s_nop 0
	s_nop 0
	s_nop 0
	s_nop 0
	s_nop 0
	v_cvt_pk_bf16_f32 v128, v122, v123
	s_nop 0
	s_nop 0
	s_nop 0
	s_nop 0
	s_nop 0
	v_cvt_pk_bf16_f32 v129, v124, v125
	s_nop 0
	s_nop 0
	s_nop 0
	s_nop 0
	s_nop 0
	v_cvt_pk_bf16_f32 v118, v118, v119
	s_nop 0
	s_nop 0
	s_nop 0
	s_nop 0
	s_nop 0
	v_cvt_pk_bf16_f32 v119, v120, v121
	s_nop 0
	s_nop 0
	s_nop 0
	s_nop 0
	s_nop 0
	v_cvt_pk_bf16_f32 v120, v110, v111
	s_nop 0
	s_nop 0
	s_nop 0
	s_nop 0
	s_nop 0
	v_lshl_or_b32 v146, s44, 8, v150
	v_cvt_pk_bf16_f32 v121, v112, v113
	v_or_b32_e32 v110, 16, v154
	v_ashrrev_i32_e32 v147, 31, v146
	v_ashrrev_i32_e32 v111, 31, v110
	v_lshl_add_u64 v[156:157], s[54:55], 0, v[156:157]
	v_lshlrev_b64 v[158:159], 1, v[146:147]
	v_lshlrev_b64 v[110:111], 11, v[110:111]
	v_lshl_add_u64 v[146:147], v[156:157], 0, v[158:159]
	v_lshl_add_u64 v[110:111], s[54:55], 0, v[110:111]
	global_store_dwordx4 v[146:147], v[118:121], off offset:256
	s_nop 0
	s_nop 0
	v_lshl_add_u64 v[118:119], v[110:111], 0, v[158:159]
	s_nop 0
	s_nop 0
	s_nop 0
	s_nop 0
	s_nop 0
	v_cvt_pk_bf16_f32 v110, v114, v115
	s_nop 0
	s_nop 0
	s_nop 0
	v_cvt_pk_bf16_f32 v111, v116, v117
	s_nop 0
	s_nop 0
	s_nop 0
	s_nop 0
	s_nop 0
	v_cvt_pk_bf16_f32 v112, v106, v107
	s_nop 0
	s_nop 0
	s_nop 0
	s_nop 0
	s_nop 0
	v_cvt_pk_bf16_f32 v113, v108, v109
	s_nop 0
	s_nop 0
	s_nop 0
	s_nop 0
	s_nop 0
	v_cvt_pk_bf16_f32 v102, v102, v103
	s_nop 0
	s_nop 0
	s_nop 0
	s_nop 0
	s_nop 0
	v_cvt_pk_bf16_f32 v103, v104, v105
	s_nop 0
	s_nop 0
	s_nop 0
	s_nop 0
	s_nop 0
	v_cvt_pk_bf16_f32 v104, v94, v95
	s_nop 0
	s_nop 0
	s_nop 0
	s_nop 0
	s_nop 0
	v_cvt_pk_bf16_f32 v105, v96, v97
	v_or_b32_e32 v94, 32, v154
	v_ashrrev_i32_e32 v95, 31, v94
	v_lshlrev_b64 v[94:95], 11, v[94:95]
	v_lshl_add_u64 v[94:95], s[54:55], 0, v[94:95]
	global_store_dwordx4 v[118:119], v[102:105], off offset:256
	s_nop 0
	s_nop 0
	v_lshl_add_u64 v[102:103], v[94:95], 0, v[158:159]
	s_nop 0
	s_nop 0
	s_nop 0
	s_nop 0
	s_nop 0
	v_cvt_pk_bf16_f32 v94, v98, v99
	s_nop 0
	s_nop 0
	s_nop 0
	v_cvt_pk_bf16_f32 v95, v100, v101
	s_nop 0
	s_nop 0
	s_nop 0
	s_nop 0
	s_nop 0
	v_cvt_pk_bf16_f32 v96, v90, v91
	s_nop 0
	s_nop 0
	s_nop 0
	s_nop 0
	s_nop 0
	v_cvt_pk_bf16_f32 v97, v92, v93
	s_nop 0
	s_nop 0
	s_nop 0
	s_nop 0
	s_nop 0
	v_cvt_pk_bf16_f32 v86, v86, v87
	s_nop 0
	s_nop 0
	s_nop 0
	s_nop 0
	s_nop 0
	v_cvt_pk_bf16_f32 v87, v88, v89
	s_nop 0
	s_nop 0
	s_nop 0
	s_nop 0
	s_nop 0
	v_cvt_pk_bf16_f32 v88, v78, v79
	s_nop 0
	s_nop 0
	s_nop 0
	s_nop 0
	s_nop 0
	v_cvt_pk_bf16_f32 v89, v80, v81
	v_or_b32_e32 v78, 48, v154
	v_ashrrev_i32_e32 v79, 31, v78
	v_lshlrev_b64 v[78:79], 11, v[78:79]
	v_lshl_add_u64 v[78:79], s[54:55], 0, v[78:79]
	global_store_dwordx4 v[102:103], v[86:89], off offset:256
	s_nop 0
	s_nop 0
	v_lshl_add_u64 v[86:87], v[78:79], 0, v[158:159]
	s_nop 0
	s_nop 0
	s_nop 0
	s_nop 0
	s_nop 0
	v_cvt_pk_bf16_f32 v78, v82, v83
	s_nop 0
	s_nop 0
	s_nop 0
	v_cvt_pk_bf16_f32 v79, v84, v85
	s_nop 0
	s_nop 0
	s_nop 0
	s_nop 0
	s_nop 0
	v_cvt_pk_bf16_f32 v80, v74, v75
	s_nop 0
	s_nop 0
	s_nop 0
	s_nop 0
	s_nop 0
	v_cvt_pk_bf16_f32 v81, v76, v77
	s_nop 0
	s_nop 0
	s_nop 0
	s_nop 0
	s_nop 0
	v_cvt_pk_bf16_f32 v70, v70, v71
	s_nop 0
	s_nop 0
	s_nop 0
	s_nop 0
	s_nop 0
	v_cvt_pk_bf16_f32 v71, v72, v73
	s_nop 0
	s_nop 0
	s_nop 0
	s_nop 0
	s_nop 0
	v_cvt_pk_bf16_f32 v72, v66, v67
	s_nop 0
	s_nop 0
	s_nop 0
	s_nop 0
	s_nop 0
	s_nop 0
	s_nop 0
	v_cvt_pk_bf16_f32 v62, v62, v63
	s_nop 0
	s_nop 0
	s_nop 0
	s_nop 0
	s_nop 0
	v_cvt_pk_bf16_f32 v63, v64, v65
	s_nop 0
	s_nop 0
	s_nop 0
	s_nop 0
	s_nop 0
	s_nop 0
	v_cvt_pk_bf16_f32 v64, v58, v59
	s_nop 0
	s_nop 0
	s_nop 0
	s_mov_b64 s[14:15], 0x40000
	s_nop 0
	s_nop 0
	v_cvt_pk_bf16_f32 v73, v68, v69
	v_lshl_add_u64 v[66:67], v[146:147], 0, s[14:15]
	s_nop 0
	s_nop 0
	s_mov_b32 s14, 0x40000
	v_cvt_pk_bf16_f32 v65, v60, v61
	v_add_co_u32_e32 v58, vcc, s14, v146
	s_mov_b64 s[14:15], 0x48000
	s_nop 0
	v_addc_co_u32_e32 v59, vcc, 0, v147, vcc
	global_store_dwordx4 v[58:59], v[62:65], off
	v_bfe_u32 v58, v54, 16, 1
	v_add3_u32 v54, v54, v58, s39
	v_bfe_u32 v58, v55, 16, 1
	v_lshrrev_b32_e32 v54, 16, v54
	v_add3_u32 v55, v55, v58, s39
	v_and_or_b32 v54, v55, s40, v54
	s_nop 0
	s_nop 0
	s_nop 0
	s_nop 0
	s_nop 0
	v_cvt_pk_bf16_f32 v55, v56, v57
	s_nop 0
	s_nop 0
	s_nop 0
	s_nop 0
	s_nop 0
	v_cvt_pk_bf16_f32 v56, v46, v47
	s_nop 0
	s_nop 0
	s_nop 0
	s_nop 0
	s_nop 0
	v_cvt_pk_bf16_f32 v57, v48, v49
	s_nop 0
	s_nop 0
	s_nop 0
	s_nop 0
	s_nop 0
	v_cvt_pk_bf16_f32 v46, v50, v51
	s_nop 0
	s_nop 0
	s_nop 0
	s_nop 0
	s_nop 0
	v_cvt_pk_bf16_f32 v47, v52, v53
	s_nop 0
	s_nop 0
	s_nop 0
	s_nop 0
	s_nop 0
	v_cvt_pk_bf16_f32 v48, v42, v43
	s_nop 0
	s_nop 0
	s_nop 0
	global_store_dwordx4 v[66:67], v[54:57], off offset:256
	s_nop 0
	s_nop 0
	v_lshl_add_u64 v[54:55], v[146:147], 0, s[14:15]
	s_mov_b32 s14, 0x48000
	v_cvt_pk_bf16_f32 v49, v44, v45
	v_add_co_u32_e32 v42, vcc, s14, v146
	s_mov_b64 s[14:15], 0x50000
	s_nop 0
	v_addc_co_u32_e32 v43, vcc, 0, v147, vcc
	global_store_dwordx4 v[42:43], v[46:49], off
	s_nop 0
	s_nop 0
	s_nop 0
	s_nop 0
	s_nop 0
	v_cvt_pk_bf16_f32 v38, v38, v39
	s_nop 0
	s_nop 0
	s_nop 0
	s_nop 0
	s_nop 0
	v_cvt_pk_bf16_f32 v39, v40, v41
	s_nop 0
	s_nop 0
	s_nop 0
	s_nop 0
	s_nop 0
	v_cvt_pk_bf16_f32 v40, v30, v31
	s_nop 0
	s_nop 0
	s_nop 0
	s_nop 0
	s_nop 0
	v_cvt_pk_bf16_f32 v41, v32, v33
	s_nop 0
	s_nop 0
	s_nop 0
	s_nop 0
	s_nop 0
	v_cvt_pk_bf16_f32 v30, v34, v35
	s_nop 0
	s_nop 0
	s_nop 0
	s_nop 0
	s_nop 0
	v_cvt_pk_bf16_f32 v31, v36, v37
	s_nop 0
	s_nop 0
	s_nop 0
	s_nop 0
	s_nop 0
	v_cvt_pk_bf16_f32 v32, v26, v27
	s_nop 0
	s_nop 0
	s_nop 0
	global_store_dwordx4 v[54:55], v[38:41], off offset:256
	s_nop 0
	s_nop 0
	v_lshl_add_u64 v[38:39], v[146:147], 0, s[14:15]
	s_mov_b32 s14, 0x50000
	v_cvt_pk_bf16_f32 v33, v28, v29
	v_add_co_u32_e32 v26, vcc, s14, v146
	s_mov_b64 s[14:15], 0x58000
	s_nop 0
	v_addc_co_u32_e32 v27, vcc, 0, v147, vcc
	global_store_dwordx4 v[26:27], v[30:33], off
	s_nop 0
	s_nop 0
	s_nop 0
	s_nop 0
	s_nop 0
	v_cvt_pk_bf16_f32 v22, v22, v23
	s_nop 0
	s_nop 0
	s_nop 0
	s_nop 0
	s_nop 0
	v_cvt_pk_bf16_f32 v23, v24, v25
	s_nop 0
	s_nop 0
	s_nop 0
	s_nop 0
	s_nop 0
	v_cvt_pk_bf16_f32 v24, v14, v15
	s_nop 0
	s_nop 0
	s_nop 0
	s_nop 0
	s_nop 0
	v_cvt_pk_bf16_f32 v25, v16, v17
	s_nop 0
	s_nop 0
	s_nop 0
	s_nop 0
	s_nop 0
	v_cvt_pk_bf16_f32 v14, v18, v19
	s_nop 0
	s_nop 0
	s_nop 0
	s_nop 0
	s_nop 0
	v_cvt_pk_bf16_f32 v15, v20, v21
	s_nop 0
	s_nop 0
	s_nop 0
	s_nop 0
	s_nop 0
	v_cvt_pk_bf16_f32 v16, v10, v11
	s_nop 0
	s_nop 0
	s_nop 0
	global_store_dwordx4 v[38:39], v[22:25], off offset:256
	s_nop 0
	s_nop 0
	v_lshl_add_u64 v[22:23], v[146:147], 0, s[14:15]
	s_mov_b32 s14, 0x58000
	v_cvt_pk_bf16_f32 v17, v12, v13
	v_add_co_u32_e32 v10, vcc, s14, v146
	global_store_dwordx4 v[146:147], v[126:129], off
	s_nop 0
	v_addc_co_u32_e32 v11, vcc, 0, v147, vcc
	global_store_dwordx4 v[10:11], v[14:17], off
	s_nop 0
	s_nop 0
	s_nop 0
	s_nop 0
	s_nop 0
	v_cvt_pk_bf16_f32 v6, v6, v7
	s_nop 0
	s_nop 0
	s_nop 0
	s_nop 0
	s_nop 0
	v_cvt_pk_bf16_f32 v7, v8, v9
	s_nop 0
	s_nop 0
	s_nop 0
	s_nop 0
	s_nop 0
	v_cvt_pk_bf16_f32 v8, v2, v3
	s_nop 0
	s_nop 0
	s_nop 0
	s_nop 0
	s_nop 0
	v_cvt_pk_bf16_f32 v9, v4, v5
	s_and_b64 vcc, exec, s[2:3]
	s_mov_b64 s[2:3], -1
	global_store_dwordx4 v[118:119], v[110:113], off
	global_store_dwordx4 v[102:103], v[94:97], off
	global_store_dwordx4 v[86:87], v[78:81], off
	global_store_dwordx4 v[86:87], v[70:73], off offset:256
	global_store_dwordx4 v[22:23], v[6:9], off offset:256
	s_cbranch_vccnz .LBB0_569
	s_andn2_b64 vcc, exec, s[6:7]
	s_cbranch_vccnz .LBB0_568
	s_barrier
	s_branch .LBB0_568

.LBB0_589:
	s_andn2_b64 vcc, exec, s[2:3]
	s_cbranch_vccnz .LBB0_594
	s_ashr_i32 s2, s33, 2
	s_mul_hi_i32 s3, s2, 0x280000
	s_mul_i32 s2, s2, 0x280000
	s_add_u32 s4, s88, s2
	s_addc_u32 s5, s89, s3
	s_add_u32 s4, s4, 0x6180000
	s_addc_u32 s5, s5, 0
	v_readfirstlane_b32 s6, v188
	s_lshr_b32 s6, s6, 6
	s_and_b32 s8, s33, 3
	s_cmp_gt_u32 s6, 3
	s_cbranch_scc1 .Lpb2_dma
	v_and_b32_e32 v2, 15, v1
	v_lshrrev_b32_e32 v3, 4, v1
	v_mul_u32_u24_e32 v4, 0x110, v2
	v_lshl_add_u32 v4, v3, 6, v4
	s_lshl_b32 s7, s6, 6
	v_lshl_add_u32 v5, v2, 2, s7
	v_mul_u32_u24_e32 v6, 4160, v3
	v_add_u32_e32 v6, v6, v5
	v_lshl_add_u32 v7, v3, 10, v5
	v_mul_u32_u24_e32 v8, 0x440, v3
	v_add_u32_e32 v8, v8, v5
	s_lshl_b32 s9, s8, 12
	s_addk_i32 s9, 0x4000
	v_add_u32_e32 v9, s9, v7
	v_mov_b32_e32 v14, 0
	ds_write_b32 v8, v14 offset:0
	ds_write_b32 v8, v14 offset:272
	ds_write_b32 v8, v14 offset:544
	ds_write_b32 v8, v14 offset:816
	s_mov_b64 s[12:13], s[4:5]
	s_mov_b32 s16, 0
	s_mov_b32 s17, 1
	s_mov_b32 s18, 0
	s_waitcnt lgkmcnt(0)
	s_barrier
	v_add_u32_e32 v11, 38912, v6
	v_add_u32_e32 v12, 9216, v7
	ds_read_b32 v36, v11 offset:0
	ds_read_b32 v37, v11 offset:256
	ds_read_b32 v38, v11 offset:512
	ds_read_b32 v39, v11 offset:768
	ds_read_b32 v40, v11 offset:1040
	ds_read_b32 v41, v11 offset:1296
	ds_read_b32 v42, v11 offset:1552
	ds_read_b32 v43, v11 offset:1808
	ds_read_b32 v44, v11 offset:2080
	ds_read_b32 v45, v11 offset:2336
	ds_read_b32 v46, v11 offset:2592
	ds_read_b32 v47, v11 offset:2848
	ds_read_b32 v48, v11 offset:3120
	ds_read_b32 v49, v11 offset:3376
	ds_read_b32 v50, v11 offset:3632
	ds_read_b32 v51, v11 offset:3888
	ds_read2st64_b32 v[52:53], v12 offset1:1
	ds_read2st64_b32 v[54:55], v12 offset0:2 offset1:3
.Lpb2_cloop:
	s_waitcnt lgkmcnt(0)
	s_barrier
	v_add_u32_e32 v10, s18, v4
	ds_read_b128 v[20:23], v10
	ds_read_b128 v[24:27], v10 offset:16
	ds_read_b128 v[28:31], v10 offset:32
	ds_read_b128 v[32:35], v10 offset:48
	s_mul_i32 s19, s17, 16640
	s_add_i32 s19, s19, 38912
	v_add_u32_e32 v11, s19, v6
	s_lshl_b32 s20, s17, 12
	s_add_i32 s20, s20, 9216
	v_add_u32_e32 v12, s20, v7
	s_sub_i32 s21, 4352, s18
	v_add_u32_e32 v13, s21, v8
	s_waitcnt lgkmcnt(0)
	v_mfma_f32_16x16x4_f32 v[56:59], v20, v36, v[52:55]
	v_mfma_f32_16x16x4_f32 v[56:59], v21, v37, v[56:59]
	ds_read_b32 v36, v11 offset:0
	v_mfma_f32_16x16x4_f32 v[56:59], v22, v38, v[56:59]
	ds_read_b32 v37, v11 offset:256
	v_mfma_f32_16x16x4_f32 v[56:59], v23, v39, v[56:59]
	ds_read_b32 v38, v11 offset:512
	v_mfma_f32_16x16x4_f32 v[56:59], v24, v40, v[56:59]
	ds_read_b32 v39, v11 offset:768
	v_mfma_f32_16x16x4_f32 v[56:59], v25, v41, v[56:59]
	ds_read_b32 v40, v11 offset:1040
	v_mfma_f32_16x16x4_f32 v[56:59], v26, v42, v[56:59]
	ds_read_b32 v41, v11 offset:1296
	v_mfma_f32_16x16x4_f32 v[56:59], v27, v43, v[56:59]
	ds_read_b32 v42, v11 offset:1552
	v_mfma_f32_16x16x4_f32 v[56:59], v28, v44, v[56:59]
	ds_read_b32 v43, v11 offset:1808
	v_mfma_f32_16x16x4_f32 v[56:59], v29, v45, v[56:59]
	ds_read_b32 v44, v11 offset:2080
	v_mfma_f32_16x16x4_f32 v[56:59], v30, v46, v[56:59]
	ds_read_b32 v45, v11 offset:2336
	v_mfma_f32_16x16x4_f32 v[56:59], v31, v47, v[56:59]
	ds_read_b32 v46, v11 offset:2592
	v_mfma_f32_16x16x4_f32 v[56:59], v32, v48, v[56:59]
	ds_read_b32 v47, v11 offset:2848
	v_mfma_f32_16x16x4_f32 v[56:59], v33, v49, v[56:59]
	ds_read_b32 v48, v11 offset:3120
	v_mfma_f32_16x16x4_f32 v[56:59], v34, v50, v[56:59]
	ds_read_b32 v49, v11 offset:3376
	v_mfma_f32_16x16x4_f32 v[56:59], v35, v51, v[56:59]
	ds_read_b32 v50, v11 offset:3632
	ds_read_b32 v51, v11 offset:3888
	ds_read2st64_b32 v[52:53], v12 offset1:1
	ds_read2st64_b32 v[54:55], v12 offset0:2 offset1:3
	s_nop 7
	ds_write_b32 v13, v56
	ds_write_b32 v13, v57 offset:272
	ds_write_b32 v13, v58 offset:544
	ds_write_b32 v13, v59 offset:816
	global_store_dword v9, v56, s[12:13]
	global_store_dword v9, v57, s[12:13] offset:256
	global_store_dword v9, v58, s[12:13] offset:512
	global_store_dword v9, v59, s[12:13] offset:768
	s_mov_b32 s18, s21
	s_add_u32 s12, s12, 0x8000
	s_addc_u32 s13, s13, 0
	s_add_i32 s17, s17, 1
	s_cmp_eq_u32 s17, 7
	s_cselect_b32 s17, 0, s17
	s_add_i32 s16, s16, 1
	s_cmp_eq_u32 s16, 79
	s_cbranch_scc0 .Lpb2_cloop
	s_waitcnt vmcnt(0) lgkmcnt(0)
	s_branch .LBB0_594
.Lpb2_dma:
	s_sub_i32 s6, s6, 4
	v_lshlrev_b32_e32 v2, 4, v1
	s_lshl_b32 s7, s6, 12
	v_add_u32_e32 v2, s7, v2
	s_lshl_b32 s9, s8, 12
	s_lshl_b32 s14, s6, 10
	s_add_i32 s9, s9, s14
	s_addk_i32 s9, 0x4000
	v_lshlrev_b32_e32 v3, 4, v1
	v_add_u32_e32 v3, s9, v3
	s_mul_i32 s14, s6, 4160
	s_add_i32 s14, s14, 38912
	s_lshl_b32 s15, s6, 10
	s_add_i32 s15, s15, 9216
	s_mov_b64 s[10:11], s[4:5]
	s_add_i32 m0, s14, 0
	s_nop 0
	global_load_lds_dwordx4 v2, s[10:11]
	s_add_i32 m0, s14, 16
	s_nop 0
	global_load_lds_dwordx4 v2, s[10:11] offset:1024
	s_add_i32 m0, s14, 32
	s_nop 0
	global_load_lds_dwordx4 v2, s[10:11] offset:2048
	s_add_i32 m0, s14, 48
	s_nop 0
	global_load_lds_dwordx4 v2, s[10:11] offset:3072
	s_add_i32 m0, s15, 0
	s_nop 0
	global_load_lds_dwordx4 v3, s[10:11]
	s_add_u32 s10, s10, 0x8000
	s_addc_u32 s11, s11, 0
	s_add_i32 m0, s14, 16640
	s_nop 0
	global_load_lds_dwordx4 v2, s[10:11]
	s_add_i32 m0, s14, 16656
	s_nop 0
	global_load_lds_dwordx4 v2, s[10:11] offset:1024
	s_add_i32 m0, s14, 16672
	s_nop 0
	global_load_lds_dwordx4 v2, s[10:11] offset:2048
	s_add_i32 m0, s14, 16688
	s_nop 0
	global_load_lds_dwordx4 v2, s[10:11] offset:3072
	s_add_i32 m0, s15, 4096
	s_nop 0
	global_load_lds_dwordx4 v3, s[10:11]
	s_add_u32 s10, s10, 0x8000
	s_addc_u32 s11, s11, 0
	s_add_i32 m0, s14, 33280
	s_nop 0
	global_load_lds_dwordx4 v2, s[10:11]
	s_add_i32 m0, s14, 33296
	s_nop 0
	global_load_lds_dwordx4 v2, s[10:11] offset:1024
	s_add_i32 m0, s14, 33312
	s_nop 0
	global_load_lds_dwordx4 v2, s[10:11] offset:2048
	s_add_i32 m0, s14, 33328
	s_nop 0
	global_load_lds_dwordx4 v2, s[10:11] offset:3072
	s_add_i32 m0, s15, 8192
	s_nop 0
	global_load_lds_dwordx4 v3, s[10:11]
	s_add_u32 s10, s10, 0x8000
	s_addc_u32 s11, s11, 0
	s_add_i32 m0, s14, 49920
	s_nop 0
	global_load_lds_dwordx4 v2, s[10:11]
	s_add_i32 m0, s14, 49936
	s_nop 0
	global_load_lds_dwordx4 v2, s[10:11] offset:1024
	s_add_i32 m0, s14, 49952
	s_nop 0
	global_load_lds_dwordx4 v2, s[10:11] offset:2048
	s_add_i32 m0, s14, 49968
	s_nop 0
	global_load_lds_dwordx4 v2, s[10:11] offset:3072
	s_add_i32 m0, s15, 12288
	s_nop 0
	global_load_lds_dwordx4 v3, s[10:11]
	s_add_u32 s10, s10, 0x8000
	s_addc_u32 s11, s11, 0
	s_add_i32 m0, s14, 66560
	s_nop 0
	global_load_lds_dwordx4 v2, s[10:11]
	s_add_i32 m0, s14, 66576
	s_nop 0
	global_load_lds_dwordx4 v2, s[10:11] offset:1024
	s_add_i32 m0, s14, 66592
	s_nop 0
	global_load_lds_dwordx4 v2, s[10:11] offset:2048
	s_add_i32 m0, s14, 66608
	s_nop 0
	global_load_lds_dwordx4 v2, s[10:11] offset:3072
	s_add_i32 m0, s15, 16384
	s_nop 0
	global_load_lds_dwordx4 v3, s[10:11]
	s_add_u32 s10, s10, 0x8000
	s_addc_u32 s11, s11, 0
	s_add_i32 m0, s14, 83200
	s_nop 0
	global_load_lds_dwordx4 v2, s[10:11]
	s_add_i32 m0, s14, 83216
	s_nop 0
	global_load_lds_dwordx4 v2, s[10:11] offset:1024
	s_add_i32 m0, s14, 83232
	s_nop 0
	global_load_lds_dwordx4 v2, s[10:11] offset:2048
	s_add_i32 m0, s14, 83248
	s_nop 0
	global_load_lds_dwordx4 v2, s[10:11] offset:3072
	s_add_i32 m0, s15, 20480
	s_nop 0
	global_load_lds_dwordx4 v3, s[10:11]
	s_add_u32 s10, s10, 0x8000
	s_addc_u32 s11, s11, 0
	s_mov_b32 s16, 0
	s_mov_b32 s18, 6
	s_waitcnt vmcnt(25)
	s_barrier
.Lpb2_dloop:
	s_waitcnt vmcnt(20)
	s_barrier
	s_mul_i32 s19, s18, 16640
	s_add_i32 s19, s19, s14
	s_add_i32 m0, s19, 0
	s_nop 0
	global_load_lds_dwordx4 v2, s[10:11]
	s_add_i32 m0, s19, 16
	s_nop 0
	global_load_lds_dwordx4 v2, s[10:11] offset:1024
	s_add_i32 m0, s19, 32
	s_nop 0
	global_load_lds_dwordx4 v2, s[10:11] offset:2048
	s_add_i32 m0, s19, 48
	s_nop 0
	global_load_lds_dwordx4 v2, s[10:11] offset:3072
	s_lshl_b32 s20, s18, 12
	s_add_i32 m0, s20, s15
	s_nop 0
	global_load_lds_dwordx4 v3, s[10:11]
	s_add_i32 s16, s16, 1
	s_cmp_lt_u32 s16, 73
	s_cselect_b32 s19, 0x8000, 0
	s_add_u32 s10, s10, s19
	s_addc_u32 s11, s11, 0
	s_add_i32 s18, s18, 1
	s_cmp_eq_u32 s18, 7
	s_cselect_b32 s18, 0, s18
	s_cmp_eq_u32 s16, 79
	s_cbranch_scc0 .Lpb2_dloop
	s_waitcnt vmcnt(0) lgkmcnt(0)
	s_branch .LBB0_594
